# attention loop trim 2: redundant lgkmcnt(0) before barriers removed, pointer increments fill the m0 wait states of the DMA block, rotated loop with one conditional back edge, next-iteration LDS addres
# speedup vs baseline: 1.0393x; 1.0019x over previous
; #define AT_BAR() do { __builtin_amdgcn_sched_barrier(0); asm volatile("s_waitcnt lgkmcnt(0)\n\ts_barrier" ::: "memory"); __builtin_amdgcn_sched_barrier(0); } while (0)
; #define AT_PIN_M() asm volatile("" : "+v"(p[0]), "+v"(p[1]), "+v"(o[0][0]), "+v"(o[0][1]), "+v"(o[1][0]), "+v"(o[1][1]))
; __device__ __forceinline__ void attn_phase(LAS unsigned char* lds, const bf16_t* Qb, const bf16_t* Kimg, const bf16_t* Vimg, bf16_t* AB, int bid, int G, int wave_k) {
;     ...
;         int b_prev = 2 * AT_BUF, b_cur = 0, b_next = AT_BUF;
;         AT_ISSUE(0, 0); AT_ISSUE(1, AT_BUF);
;         asm volatile("s_waitcnt vmcnt(0)" ::: "memory"); AT_BAR();
;         if (grpB) AT_BAR();
;         for (int t = 0; t < 256; ++t) {
;             AT_MSEG(b_cur, 0, (t > 0 ? b_prev : b_cur), 2);
;             AT_PIN_M();
;             AT_BAR();
;             AT_SM(t == 0);
;             AT_BAR();
;             const bool issued = (t + 2 < 256);
;             if (issued) AT_ISSUE(t + 2, b_prev);
.LBB0_962:
	s_waitcnt lgkmcnt(0)
	s_barrier
	s_add_u32 s0, s0, 0x6000
	s_addc_u32 s1, s1, 0
	s_mul_i32 s16, s55, 3
	s_add_u32 s18, s18, s16
	s_addc_u32 s19, s19, 0
	s_add_u32 s20, s20, 0x9000
	s_addc_u32 s21, s21, 0
	s_mov_b32 s61, 1
	s_mov_b32 s63, 0xa000
	s_movk_i32 s62, 0x5000
	s_mov_b32 s16, 0
	v_mov_b32_e32 v65, v64
	v_mov_b32_e32 v66, v64
	v_mov_b32_e32 v67, v64
	v_mov_b32_e32 v68, v64
	v_mov_b32_e32 v69, v64
	v_mov_b32_e32 v70, v64
	v_mov_b32_e32 v71, v64
	v_mov_b32_e32 v72, v64
	v_mov_b32_e32 v73, v64
	v_mov_b32_e32 v74, v64
	v_mov_b32_e32 v75, v64
	v_mov_b32_e32 v76, v64
	v_mov_b32_e32 v77, v64
	v_mov_b32_e32 v78, v64
	v_mov_b32_e32 v79, v64
	v_mov_b32_e32 v234, v223
	v_mov_b32_e32 v237, v222
	s_mov_b32 s64, s16
	v_add_u32_e32 v160, s62, v236
	v_add_u32_e32 v128, s64, v236
.LBB0_963:
	ds_read_b128 v[104:107], v160
	ds_read_b128 v[108:111], v160 offset:2048
	ds_read_b128 v[120:123], v160 offset:4096
	ds_read_b128 v[124:127], v160 offset:6144
	ds_read_b128 v[210:213], v160 offset:8192
	ds_read_b128 v[230:233], v160 offset:10240
	ds_read_b128 v[238:241], v128 offset:16384
	ds_read_b128 v[242:245], v128 offset:16896
	ds_read_b128 v[246:249], v128 offset:18432
	ds_read_b128 v[250:253], v128 offset:18944
	s_setprio 1
	s_waitcnt lgkmcnt(9)
	v_mfma_f32_32x32x16_bf16 v[144:159], v[104:107], v[162:165], v[64:79]
	v_mfma_f32_32x32x16_bf16 v[128:143], v[104:107], v[186:189], v[80:95]
	s_waitcnt lgkmcnt(7)
	v_mfma_f32_32x32x16_bf16 v[144:159], v[108:111], v[166:169], v[144:159]
	v_mfma_f32_32x32x16_bf16 v[128:143], v[108:111], v[190:193], v[128:143]
	v_mfma_f32_32x32x16_bf16 v[144:159], v[120:123], v[170:173], v[144:159]
	v_mfma_f32_32x32x16_bf16 v[128:143], v[120:123], v[194:197], v[128:143]
	s_waitcnt lgkmcnt(4)
	v_mfma_f32_32x32x16_bf16 v[144:159], v[124:127], v[174:177], v[144:159]
	v_mfma_f32_32x32x16_bf16 v[128:143], v[124:127], v[198:201], v[128:143]
	v_mfma_f32_32x32x16_bf16 v[144:159], v[210:213], v[178:181], v[144:159]
	v_mfma_f32_32x32x16_bf16 v[128:143], v[210:213], v[202:205], v[128:143]
	v_mfma_f32_32x32x16_bf16 v[144:159], v[230:233], v[182:185], v[144:159]
	v_mfma_f32_32x32x16_bf16 v[128:143], v[230:233], v[206:209], v[128:143]
	s_waitcnt lgkmcnt(0)
	v_mfma_f32_32x32x16_bf16 v[48:63], v[238:241], v[116:119], v[48:63]
	v_mfma_f32_32x32x16_bf16 v[32:47], v[242:245], v[116:119], v[32:47]
	v_mfma_f32_32x32x16_bf16 v[16:31], v[238:241], v[100:103], v[16:31]
	v_mfma_f32_32x32x16_bf16 v[0:15], v[242:245], v[100:103], v[0:15]
	v_mfma_f32_32x32x16_bf16 v[48:63], v[246:249], v[112:115], v[48:63]
	v_mfma_f32_32x32x16_bf16 v[32:47], v[250:253], v[112:115], v[32:47]
	v_mfma_f32_32x32x16_bf16 v[16:31], v[246:249], v[96:99], v[16:31]
	v_mfma_f32_32x32x16_bf16 v[0:15], v[250:253], v[96:99], v[0:15]
	s_setprio 0
	s_barrier
	s_nop 1
	v_exp_f32_e32 v144, v144
	v_exp_f32_e32 v145, v145
	v_exp_f32_e32 v146, v146
	v_exp_f32_e32 v147, v147
	v_add_f32_e32 v210, v144, v145
	v_exp_f32_e32 v148, v148
	v_add_f32_e32 v210, v210, v146
	v_exp_f32_e32 v149, v149
	v_add_f32_e32 v210, v210, v147
	v_exp_f32_e32 v150, v150
	v_add_f32_e32 v210, v210, v148
	v_exp_f32_e32 v151, v151
	v_add_f32_e32 v210, v210, v149
	v_exp_f32_e32 v152, v152
	v_add_f32_e32 v210, v210, v150
	v_exp_f32_e32 v153, v153
	v_add_f32_e32 v210, v210, v151
	v_exp_f32_e32 v154, v154
	v_add_f32_e32 v210, v210, v152
	v_exp_f32_e32 v155, v155
	v_add_f32_e32 v210, v210, v153
	v_exp_f32_e32 v156, v156
	v_add_f32_e32 v210, v210, v154
	v_exp_f32_e32 v157, v157
	v_add_f32_e32 v210, v210, v155
	v_exp_f32_e32 v158, v158
	v_add_f32_e32 v210, v210, v156
	v_exp_f32_e32 v159, v159
	v_add_f32_e32 v210, v210, v157
	v_add_f32_e32 v210, v210, v158
	v_add_f32_e32 v210, v210, v159
	v_exp_f32_e32 v128, v128
	v_exp_f32_e32 v129, v129
	v_exp_f32_e32 v130, v130
	v_exp_f32_e32 v131, v131
	v_add_f32_e32 v211, v128, v129
	v_exp_f32_e32 v132, v132
	v_add_f32_e32 v211, v211, v130
	v_exp_f32_e32 v133, v133
	v_add_f32_e32 v211, v211, v131
	v_exp_f32_e32 v134, v134
	v_add_f32_e32 v211, v211, v132
	v_exp_f32_e32 v135, v135
	v_add_f32_e32 v211, v211, v133
	v_exp_f32_e32 v136, v136
	v_add_f32_e32 v211, v211, v134
	v_exp_f32_e32 v137, v137
	v_add_f32_e32 v211, v211, v135
	v_exp_f32_e32 v138, v138
	v_add_f32_e32 v211, v211, v136
	v_exp_f32_e32 v139, v139
	v_add_f32_e32 v211, v211, v137
	v_exp_f32_e32 v140, v140
	v_add_f32_e32 v211, v211, v138
	v_exp_f32_e32 v141, v141
	v_add_f32_e32 v211, v211, v139
	v_exp_f32_e32 v142, v142
	v_add_f32_e32 v211, v211, v140
	v_exp_f32_e32 v143, v143
	v_add_f32_e32 v211, v211, v141
	v_add_f32_e32 v211, v211, v142
	v_add_f32_e32 v211, v211, v143
	v_max_f32_e32 v212, v210, v211
	v_cmp_lt_f32_e32 vcc, 0x43800000, v212
	s_cbranch_vccnz .Lph_rare_a
.Lph_cont_a:
	v_add_f32_e32 v234, v234, v210
	v_add_f32_e32 v237, v237, v211
	v_cvt_pk_bf16_f32 v151, v150, v151
	v_cvt_pk_bf16_f32 v150, v148, v149
	v_cvt_pk_bf16_f32 v149, v146, v147
	v_cvt_pk_bf16_f32 v148, v144, v145
	v_cvt_pk_bf16_f32 v144, v152, v153
	v_cvt_pk_bf16_f32 v145, v154, v155
	v_cvt_pk_bf16_f32 v146, v156, v157
	v_cvt_pk_bf16_f32 v147, v158, v159
	v_cvt_pk_bf16_f32 v135, v134, v135
	v_cvt_pk_bf16_f32 v134, v132, v133
	v_cvt_pk_bf16_f32 v133, v130, v131
	v_cvt_pk_bf16_f32 v132, v128, v129
	v_cvt_pk_bf16_f32 v128, v136, v137
	v_cvt_pk_bf16_f32 v129, v138, v139
	v_cvt_pk_bf16_f32 v130, v140, v141
	v_cvt_pk_bf16_f32 v131, v142, v143
	s_waitcnt vmcnt(0)
	s_barrier
	s_cmpk_gt_u32 s61, 0xfd
	s_cbranch_scc1 .LBB0_969
	s_add_i32 m0, s54, s64
	s_bitcmp1_b32 s42, 0
	global_load_lds_dwordx4 v218, s[20:21]
	s_add_i32 m0, m0, 0x2000
	s_add_u32 s20, s20, 0x3000
	s_addc_u32 s21, s21, 0
	global_load_lds_dwordx4 v218, s[18:19]
	s_add_u32 s18, s18, s55
	s_addc_u32 s19, s19, 0
	s_bitcmp1_b32 s42, 0
	s_cbranch_scc1 .LBB0_969
	s_add_i32 m0, m0, 0x2000
	s_nop 0
	global_load_lds_dwordx4 v218, s[0:1]
	s_add_u32 s0, s0, 0x2000
	s_addc_u32 s1, s1, 0

.LBB0_974:
	s_barrier
	v_add_u32_e32 v160, s63, v236
	v_add_u32_e32 v128, s62, v236
	v_exp_f32_e32 v112, v112
	v_exp_f32_e32 v113, v113
	v_exp_f32_e32 v114, v114
	v_exp_f32_e32 v115, v115
	v_add_f32_e32 v210, v112, v113
	v_exp_f32_e32 v116, v116
	v_add_f32_e32 v210, v210, v114
	v_exp_f32_e32 v117, v117
	v_add_f32_e32 v210, v210, v115
	v_exp_f32_e32 v118, v118
	v_add_f32_e32 v210, v210, v116
	v_exp_f32_e32 v119, v119
	v_add_f32_e32 v210, v210, v117
	v_exp_f32_e32 v120, v120
	v_add_f32_e32 v210, v210, v118
	v_exp_f32_e32 v121, v121
	v_add_f32_e32 v210, v210, v119
	v_exp_f32_e32 v122, v122
	v_add_f32_e32 v210, v210, v120
	v_exp_f32_e32 v123, v123
	v_add_f32_e32 v210, v210, v121
	v_exp_f32_e32 v124, v124
	v_add_f32_e32 v210, v210, v122
	v_exp_f32_e32 v125, v125
	v_add_f32_e32 v210, v210, v123
	v_exp_f32_e32 v126, v126
	v_add_f32_e32 v210, v210, v124
	v_exp_f32_e32 v127, v127
	v_add_f32_e32 v210, v210, v125
	v_add_f32_e32 v210, v210, v126
	v_add_f32_e32 v210, v210, v127
	v_exp_f32_e32 v96, v96
	v_exp_f32_e32 v97, v97
	v_exp_f32_e32 v98, v98
	v_exp_f32_e32 v99, v99
	v_add_f32_e32 v211, v96, v97
	v_exp_f32_e32 v100, v100
	v_add_f32_e32 v211, v211, v98
	v_exp_f32_e32 v101, v101
	v_add_f32_e32 v211, v211, v99
	v_exp_f32_e32 v102, v102
	v_add_f32_e32 v211, v211, v100
	v_exp_f32_e32 v103, v103
	v_add_f32_e32 v211, v211, v101
	v_exp_f32_e32 v104, v104
	v_add_f32_e32 v211, v211, v102
	v_exp_f32_e32 v105, v105
	v_add_f32_e32 v211, v211, v103
	v_exp_f32_e32 v106, v106
	v_add_f32_e32 v211, v211, v104
	v_exp_f32_e32 v107, v107
	v_add_f32_e32 v211, v211, v105
	v_exp_f32_e32 v108, v108
	v_add_f32_e32 v211, v211, v106
	v_exp_f32_e32 v109, v109
	v_add_f32_e32 v211, v211, v107
	v_exp_f32_e32 v110, v110
	v_add_f32_e32 v211, v211, v108
	v_exp_f32_e32 v111, v111
	v_add_f32_e32 v211, v211, v109
	v_add_f32_e32 v211, v211, v110
	v_add_f32_e32 v211, v211, v111
	v_max_f32_e32 v212, v210, v211
	v_cmp_lt_f32_e32 vcc, 0x43800000, v212
	s_cbranch_vccnz .Lph_rare_b

; #define AT_BAR() do { __builtin_amdgcn_sched_barrier(0); asm volatile("s_waitcnt lgkmcnt(0)\n\ts_barrier" ::: "memory"); __builtin_amdgcn_sched_barrier(0); } while (0)
; __device__ __forceinline__ void attn_phase(LAS unsigned char* lds, const bf16_t* Qb, const bf16_t* Kimg, const bf16_t* Vimg, bf16_t* AB, int bid, int G, int wave_k) {
;     ...
;             AT_BAR();
;             const int tmp = b_prev; b_prev = b_cur; b_cur = b_next; b_next = tmp;
;         }
.LBB0_981:
	s_barrier
	s_add_i32 s61, s61, 1
	s_mov_b32 s16, s62
	s_mov_b32 s62, s63
	s_mov_b32 s63, s64
	s_mov_b32 s64, s16
	s_cmpk_lg_i32 s61, 0x100
	s_cbranch_scc1 .LBB0_963
	s_branch .LBB0_983

; #define AT_BAR() do { __builtin_amdgcn_sched_barrier(0); asm volatile("s_waitcnt lgkmcnt(0)\n\ts_barrier" ::: "memory"); __builtin_amdgcn_sched_barrier(0); } while (0)
; __device__ __forceinline__ void attn_phase(LAS unsigned char* lds, const bf16_t* Qb, const bf16_t* Kimg, const bf16_t* Vimg, bf16_t* AB, int bid, int G, int wave_k) {
;     ...
;             const int tmp = b_prev; b_prev = b_cur; b_cur = b_next; b_next = tmp;
;         }
;         AT_PV(b_prev, 2);
;         if (!grpB) AT_BAR();
;         AT_BAR();
.LBB0_983:
	v_mov_b32_e32 v223, v234
	v_mov_b32_e32 v222, v237
	v_add_u32_e32 v72, s64, v236
	ds_read_b128 v[64:67], v72 offset:16384
	ds_read_b128 v[68:71], v72 offset:16896
	s_and_b64 vcc, s[14:15], exec
	s_waitcnt lgkmcnt(0)
	v_mfma_f32_32x32x16_bf16 v[48:63], v[64:67], v[116:119], v[48:63]
	v_mfma_f32_32x32x16_bf16 v[32:47], v[68:71], v[116:119], v[32:47]
	v_mfma_f32_32x32x16_bf16 v[16:31], v[64:67], v[100:103], v[16:31]
	v_mfma_f32_32x32x16_bf16 v[0:15], v[68:71], v[100:103], v[0:15]
	ds_read_b128 v[64:67], v72 offset:18432
	ds_read_b128 v[68:71], v72 offset:18944
	s_waitcnt lgkmcnt(0)
	v_mfma_f32_32x32x16_bf16 v[48:63], v[64:67], v[112:115], v[48:63]
	v_mfma_f32_32x32x16_bf16 v[32:47], v[68:71], v[112:115], v[32:47]
	v_mfma_f32_32x32x16_bf16 v[16:31], v[64:67], v[96:99], v[16:31]
	v_mfma_f32_32x32x16_bf16 v[0:15], v[68:71], v[96:99], v[0:15]
	s_cbranch_vccz .LBB0_947
	s_waitcnt lgkmcnt(0)
	s_barrier
	s_branch .LBB0_947
